# lora: one wave per 16-token item again (no wave-pair split; sample items on wave 4 run concurrently), L2 warm-up kept
# baseline (speedup 1.0000x reference)
; #define LAS __attribute__((address_space(3)))
; __device__ __forceinline__ float sigmoidf_(float x) { return frcp(1.f + fexp2(-1.4426950408889634f * x)); }
;     __device__ __forceinline__ const float* in(int i) const { return (const float*)ptr(i); }
;     __device__ __forceinline__ unsigned char* ws() const { return (unsigned char*)ptr(37); }
; #define ws (p.ws())
; __device__ __forceinline__ void phase_lora(const Ctx& p, LAS unsigned char* lds) {
;     const int tid = threadIdx.x, lane = tid & 63, wave = __builtin_amdgcn_readfirstlane(tid >> 6), q = lane & 15, g = lane >> 4;
;     const bf16_t* ZRW = (const bf16_t*)(p.ws() + WS_ZRW);
;     float* DEC = (float*)(p.ws() + WS_DEC); bf16_t* AB = (bf16_t*)(p.ws() + WS_ABUF); bf16_t* GG = (bf16_t*)(p.ws() + WS_GG);
;     const bf16_t* w2T = (const bf16_t*)(p.ws() + WS_LW); const bf16_t* a2T = w2T + 512 * 64; const bf16_t* g2T = a2T + 512 * 64;
;     LAS bf16_t* X = (LAS bf16_t*)(lds + wave * 16 * 264 * 2);
;     const float* mu = p.in(17) + 1536;
;     for (int it = blockIdx.x + gridDim.x * wave; it < MR / 16; it += gridDim.x * 8) {
;         const int r0 = it * 16;
;         {
;             const int tt = lane >> 2, cq = lane & 3, row = r0 + tt;
; #pragma unroll
;             for (int j = 0; j < 8; ++j) {
;                 const int c = cq * 64 + j * 8;
;                 float m8[8], z[8];
; #pragma unroll
;                 for (int e = 0; e < 8; ++e) m8[e] = mu[c + e];
;                 zshift8(p, ZRW, row, 1536 + c, m8, z);
; #pragma unroll
;                 for (int e = 0; e < 8; ++e) z[e] = cq == 0 ? tanhf(z[e]) : (cq == 1 ? z[e] : sigmoidf_(z[e]));
.LBB0_870:
	s_cmp_lt_i32 s36, 6
	s_cselect_b64 s[4:5], -1, 0
	s_and_b64 s[10:11], s[4:5], s[2:3]
	s_andn2_b64 vcc, exec, s[10:11]
	s_cbranch_vccnz .LBB0_1564
	s_waitcnt vmcnt(0)
	v_mov_b32_e32 v0, 0x23528
	v_mov_b32_e32 v1, 0x23488
	v_mov_b32_e32 v2, 0x23428
	v_mov_b32_e32 v3, 0x23490
	v_mov_b32_e32 v4, 0x234a0
	ds_read_b64 v[6:7], v0
	ds_read_b64 v[8:9], v1
	ds_read_b64 v[10:11], v2
	ds_read_b64 v[12:13], v3
	ds_read_b64 v[14:15], v4
	v_readfirstlane_b32 s2, v180
	s_waitcnt lgkmcnt(0)
	v_readfirstlane_b32 s12, v6
	v_readfirstlane_b32 s13, v7
	v_readfirstlane_b32 s16, v8
	v_readfirstlane_b32 s17, v9
	v_readfirstlane_b32 s18, v10
	v_readfirstlane_b32 s19, v11
	v_readfirstlane_b32 s20, v12
	v_readfirstlane_b32 s21, v13
	v_readfirstlane_b32 s22, v14
	v_readfirstlane_b32 s23, v15
	s_nop 4
	s_lshr_b32 s27, s2, 6
	s_mov_b32 s56, 0
	s_mul_i32 s2, s27, s38
	s_add_i32 s26, s2, s28
	s_add_u32 s14, s12, 0x8340000
	s_addc_u32 s15, s13, 0
	s_add_u32 s16, s16, 0x1800
	s_addc_u32 s17, s17, 0
	s_add_u32 s24, s12, 0x3110000
	s_addc_u32 s25, s13, 0
	s_add_u32 s40, s12, 0x3120000
	s_addc_u32 s41, s13, 0
	s_add_u32 s42, s12, 0x3130000
	s_addc_u32 s43, s13, 0
	s_add_u32 s44, s12, 0x3200000
	s_addc_u32 s45, s13, 0
	s_add_u32 s46, s12, 0x4240000
	s_addc_u32 s47, s13, 0
	s_add_u32 s54, s12, 0xfd20000
	s_addc_u32 s55, s13, 0
	v_and_b32_e32 v0, 63, v180
	v_lshrrev_b32_e32 v1, 2, v0
	v_and_b32_e32 v2, 3, v0
	v_and_b32_e32 v10, 15, v0
	v_lshrrev_b32_e32 v11, 4, v0
	v_cmp_eq_u32_e32 vcc, 0, v2
	v_mov_b32_e32 v12, 0xbfb8aa3b
	v_mov_b32_e32 v13, 0x4038aa3b
	v_cndmask_b32_e32 v7, v12, v13, vcc
	v_mov_b32_e32 v12, 1.0
	v_mov_b32_e32 v13, -2.0
	v_cndmask_b32_e32 v8, v12, v13, vcc
	v_mov_b32_e32 v12, 0
	v_mov_b32_e32 v13, 1.0
	v_cndmask_b32_e32 v9, v12, v13, vcc
	v_cmp_eq_u32_e64 s[48:49], 1, v2
	s_mul_i32 s3, s27, 0x2100
	v_mul_u32_u24_e32 v6, 0x210, v1
	v_lshl_add_u32 v6, v2, 7, v6
	v_add_u32_e32 v6, s3, v6
	v_mul_u32_u24_e32 v14, 0x210, v10
	v_lshl_add_u32 v14, v11, 4, v14
	v_add_u32_e32 v14, s3, v14
	v_lshlrev_b32_e32 v5, 8, v2
	s_lshr_b32 s2, s28, 3
	s_and_b32 s2, s2, 31
	s_lshl_b32 s2, s2, 13
	v_lshlrev_b32_e32 v12, 4, v180
	v_add_u32_e32 v12, s2, v12
	v_and_b32_e32 v13, 0x7f, v180
	v_lshlrev_b32_e32 v13, 4, v13
	global_load_dwordx4 v[164:167], v12, s[24:25]
	global_load_dwordx4 v[168:171], v13, s[20:21]
	global_load_dwordx4 v[172:175], v13, s[22:23]

; #define LAS __attribute__((address_space(3)))
; __device__ __forceinline__ unsigned pk2(float lo, float hi) { f32x2 v = {lo, hi}; bf16x2_t b = __builtin_convertvector(v, bf16x2_t); return __builtin_bit_cast(unsigned, b); }
; __device__ __forceinline__ float sigmoidf_(float x) { return frcp(1.f + fexp2(-1.4426950408889634f * x)); }
;     __device__ __forceinline__ const float* in(int i) const { return (const float*)ptr(i); }
; __device__ __forceinline__ void phase_lora(const Ctx& p, LAS unsigned char* lds) {
;     ...
;                 zshift8(p, ZRW, row, 1536 + c, m8, z);
; #pragma unroll
;                 for (int e = 0; e < 8; ++e) z[e] = cq == 0 ? tanhf(z[e]) : (cq == 1 ? z[e] : sigmoidf_(z[e]));
;                 u32x4 w; w.x = pk2(z[0], z[1]); w.y = pk2(z[2], z[3]); w.z = pk2(z[4], z[5]); w.w = pk2(z[6], z[7]);
;                 *(LAS u32x4*)(X + tt * 264 + c) = w;
;             }
;         }
;         asm volatile("s_waitcnt lgkmcnt(0)" ::: "memory");
;         bf16x8 bx[8];
; #pragma unroll
;         for (int ks = 0; ks < 8; ++ks) bx[ks] = *(const LAS bf16x8*)(X + q * 264 + ks * 32 + 8 * g);
;         const int row = r0 + q;
;         struct WF { bf16x8 w[2], a[2], gq[4]; f32x4 w0, a0; };
;         auto ldw = [&](WF& f, int nt) {
;             const int n = nt * 16 + q, c = nt * 16 + 4 * g;
; #pragma unroll
;             for (int ks = 0; ks < 2; ++ks) { f.w[ks] = *(const bf16x8*)(w2T + n * 64 + ks * 32 + 8 * g); f.a[ks] = *(const bf16x8*)(a2T + n * 64 + ks * 32 + 8 * g); }
; #pragma unroll
;             for (int ks = 0; ks < 4; ++ks) f.gq[ks] = *(const bf16x8*)(g2T + n * 128 + ks * 32 + 8 * g);
;             f.w0 = *(const f32x4*)(p.in(18) + c); f.a0 = *(const f32x4*)(p.in(20) + c);
.Llora_nf7:
	v_sub_f32_e32 v152, v152, v144
	v_sub_f32_e32 v153, v153, v145
	v_sub_f32_e32 v154, v154, v146
	v_sub_f32_e32 v155, v155, v147
	v_sub_f32_e32 v156, v156, v148
	v_sub_f32_e32 v157, v157, v149
	v_sub_f32_e32 v158, v158, v150
	v_sub_f32_e32 v159, v159, v151
	v_fmac_f32_e32 v144, v152, v136
	v_fmac_f32_e32 v145, v153, v137
	v_fmac_f32_e32 v146, v154, v138
	v_fmac_f32_e32 v147, v155, v139
	v_fmac_f32_e32 v148, v156, v140
	v_fmac_f32_e32 v149, v157, v141
	v_fmac_f32_e32 v150, v158, v142
	v_fmac_f32_e32 v151, v159, v143
	v_mul_f32_e32 v152, v7, v144
	v_mul_f32_e32 v153, v7, v145
	v_mul_f32_e32 v154, v7, v146
	v_mul_f32_e32 v155, v7, v147
	v_mul_f32_e32 v156, v7, v148
	v_mul_f32_e32 v157, v7, v149
	v_mul_f32_e32 v158, v7, v150
	v_mul_f32_e32 v159, v7, v151
	v_exp_f32_e32 v152, v152
	v_exp_f32_e32 v153, v153
	v_exp_f32_e32 v154, v154
	v_exp_f32_e32 v155, v155
	v_exp_f32_e32 v156, v156
	v_exp_f32_e32 v157, v157
	v_exp_f32_e32 v158, v158
	v_exp_f32_e32 v159, v159
	v_add_f32_e32 v152, 1.0, v152
	v_add_f32_e32 v153, 1.0, v153
	v_add_f32_e32 v154, 1.0, v154
	v_add_f32_e32 v155, 1.0, v155
	v_add_f32_e32 v156, 1.0, v156
	v_add_f32_e32 v157, 1.0, v157
	v_add_f32_e32 v158, 1.0, v158
	v_add_f32_e32 v159, 1.0, v159
	v_rcp_f32_e32 v152, v152
	v_rcp_f32_e32 v153, v153
	v_rcp_f32_e32 v154, v154
	v_rcp_f32_e32 v155, v155
	v_rcp_f32_e32 v156, v156
	v_rcp_f32_e32 v157, v157
	v_rcp_f32_e32 v158, v158
	v_rcp_f32_e32 v159, v159
	v_fma_f32 v152, v152, v8, v9
	v_fma_f32 v153, v153, v8, v9
	v_fma_f32 v154, v154, v8, v9
	v_fma_f32 v155, v155, v8, v9
	v_fma_f32 v156, v156, v8, v9
	v_fma_f32 v157, v157, v8, v9
	v_fma_f32 v158, v158, v8, v9
	v_fma_f32 v159, v159, v8, v9
	v_cndmask_b32_e64 v152, v152, v144, s[48:49]
	v_cndmask_b32_e64 v153, v153, v145, s[48:49]
	v_cndmask_b32_e64 v154, v154, v146, s[48:49]
	v_cndmask_b32_e64 v155, v155, v147, s[48:49]
	v_cndmask_b32_e64 v156, v156, v148, s[48:49]
	v_cndmask_b32_e64 v157, v157, v149, s[48:49]
	v_cndmask_b32_e64 v158, v158, v150, s[48:49]
	v_cndmask_b32_e64 v159, v159, v151, s[48:49]
	v_cvt_pk_bf16_f32 v160, v152, v153
	v_cvt_pk_bf16_f32 v161, v154, v155
	v_cvt_pk_bf16_f32 v162, v156, v157
	v_cvt_pk_bf16_f32 v163, v158, v159
	ds_write_b128 v6, v[160:163] offset:112
	s_waitcnt lgkmcnt(0)
	ds_read_b128 v[184:187], v14 offset:0
	ds_read_b128 v[188:191], v14 offset:64
	ds_read_b128 v[192:195], v14 offset:128
	ds_read_b128 v[196:199], v14 offset:192
	ds_read_b128 v[200:203], v14 offset:256
	ds_read_b128 v[204:207], v14 offset:320
	ds_read_b128 v[208:211], v14 offset:384
	ds_read_b128 v[212:215], v14 offset:448
	s_lshl_b32 s2, s26, 4
	v_add_u32_e32 v137, s2, v10
	v_lshlrev_b32_e32 v132, 7, v10
	v_lshl_add_u32 v132, v11, 4, v132
	v_lshlrev_b32_e32 v133, 8, v10
	v_lshl_add_u32 v133, v11, 4, v133
	v_lshlrev_b32_e32 v134, 4, v11
	v_lshlrev_b32_e32 v135, 11, v137
	v_lshl_add_u32 v135, v11, 4, v135
	v_lshlrev_b32_e32 v136, 10, v137
	v_lshl_add_u32 v136, v11, 3, v136
	s_lshl_b32 s2, s56, 15
	v_add_u32_e32 v132, s2, v132
	s_lshl_b32 s2, s56, 16
	v_add_u32_e32 v133, s2, v133
	s_lshl_b32 s2, s56, 10
	v_add_u32_e32 v134, s2, v134
	v_add_u32_e32 v135, s2, v135
	s_lshl_b32 s2, s56, 9
	v_add_u32_e32 v136, s2, v136
	global_load_dwordx4 v[16:19], v132, s[24:25]
	global_load_dwordx4 v[20:23], v132, s[24:25] offset:64
	global_load_dwordx4 v[24:27], v132, s[40:41]
	global_load_dwordx4 v[28:31], v132, s[40:41] offset:64
	global_load_dwordx4 v[32:35], v133, s[42:43]
	global_load_dwordx4 v[36:39], v133, s[42:43] offset:64
	global_load_dwordx4 v[40:43], v133, s[42:43] offset:128
	global_load_dwordx4 v[44:47], v133, s[42:43] offset:192
	global_load_dwordx4 v[48:51], v134, s[20:21]
	global_load_dwordx4 v[52:55], v134, s[22:23]
	v_add_u32_e32 v132, 0x800, v132
	v_add_u32_e32 v133, 0x1000, v133
	v_add_u32_e32 v134, 64, v134
	s_waitcnt lgkmcnt(0)
	global_load_dwordx4 v[56:59], v132, s[24:25]
	global_load_dwordx4 v[60:63], v132, s[24:25] offset:64
	global_load_dwordx4 v[64:67], v132, s[40:41]
	global_load_dwordx4 v[68:71], v132, s[40:41] offset:64
	global_load_dwordx4 v[72:75], v133, s[42:43]
	global_load_dwordx4 v[76:79], v133, s[42:43] offset:64
	global_load_dwordx4 v[80:83], v133, s[42:43] offset:128
	global_load_dwordx4 v[84:87], v133, s[42:43] offset:192
	global_load_dwordx4 v[88:91], v134, s[20:21]
	global_load_dwordx4 v[92:95], v134, s[22:23]
	s_waitcnt vmcnt(10)
; __device__ __forceinline__ unsigned pk2(float lo, float hi) { f32x2 v = {lo, hi}; bf16x2_t b = __builtin_convertvector(v, bf16x2_t); return __builtin_bit_cast(unsigned, b); }
; __device__ __forceinline__ float sigmoidf_(float x) { return frcp(1.f + fexp2(-1.4426950408889634f * x)); }
; __device__ __forceinline__ void phase_lora(const Ctx& p, LAS unsigned char* lds) {
;     ...
;         auto tile = [&](const WF& f, int nt) {
;             f32x4 aw = (f32x4){0.f, 0.f, 0.f, 0.f}, aa = aw, ag = aw;
; #pragma unroll
;             for (int ks = 0; ks < 2; ++ks) { aw = __builtin_amdgcn_mfma_f32_16x16x32_bf16(f.w[ks], bx[ks], aw, 0, 0, 0); aa = __builtin_amdgcn_mfma_f32_16x16x32_bf16(f.a[ks], bx[2 + ks], aa, 0, 0, 0); }
; #pragma unroll
;             for (int ks = 0; ks < 4; ++ks) ag = __builtin_amdgcn_mfma_f32_16x16x32_bf16(f.gq[ks], bx[4 + ks], ag, 0, 0, 0);
;             const int c = nt * 16 + 4 * g;
;             f32x4 dec; float av[4];
; #pragma unroll
;             for (int e = 0; e < 4; ++e) {
;                 const float x = f.w0[e] + aw[e];
;                 const float sp = fmaxf(-x, 0.f) + log1pf(expf(-fabsf(x)));
;                 dec[e] = expf(-expf(-sp - 0.5f));
;                 av[e] = sigmoidf_(f.a0[e] + aa[e]);
;             }
;             *(f32x4*)(DEC + (size_t)row * 512 + c) = dec;
;             *(u32x2*)(AB + (size_t)row * 512 + c) = (u32x2){pk2(av[0], av[1]), pk2(av[2], av[3])};
;             *(u32x2*)(GG + (size_t)row * 512 + c) = (u32x2){pk2(ag[0], ag[1]), pk2(ag[2], ag[3])};
;         };
;         WF fa, fb;
;         ldw(fa, 0);
; #pragma unroll 1
;         for (int nt = 0; nt < 32; nt += 2) {
;             ldw(fb, nt + 1);
;             tile(fa, nt);
;             ldw(fa, (nt + 2) & 31);
;             tile(fb, nt + 1);
;         }
	v_mfma_f32_16x16x32_bf16 v[96:99], v[16:19], v[184:187], 0
	v_mfma_f32_16x16x32_bf16 v[100:103], v[24:27], v[192:195], 0
	v_mfma_f32_16x16x32_bf16 v[104:107], v[32:35], v[200:203], 0
	v_mfma_f32_16x16x32_bf16 v[96:99], v[20:23], v[188:191], v[96:99]
	v_mfma_f32_16x16x32_bf16 v[100:103], v[28:31], v[196:199], v[100:103]
	v_mfma_f32_16x16x32_bf16 v[104:107], v[36:39], v[204:207], v[104:107]
	v_mfma_f32_16x16x32_bf16 v[104:107], v[40:43], v[208:211], v[104:107]
	v_mfma_f32_16x16x32_bf16 v[104:107], v[44:47], v[212:215], v[104:107]
	v_add_u32_e32 v132, 0x800, v132
	v_add_u32_e32 v133, 0x1000, v133
	v_add_u32_e32 v134, 64, v134
	s_nop 4
	v_add_f32_e32 v108, v48, v96
	v_add_f32_e32 v109, v49, v97
	v_add_f32_e32 v110, v50, v98
	v_add_f32_e32 v111, v51, v99
	v_add_f32_e32 v112, v52, v100
	v_add_f32_e32 v113, v53, v101
	v_add_f32_e32 v114, v54, v102
	v_add_f32_e32 v115, v55, v103
	v_mul_f32_e32 v108, 0xbfb8aa3b, v108
	v_mul_f32_e32 v109, 0xbfb8aa3b, v109
	v_mul_f32_e32 v110, 0xbfb8aa3b, v110
	v_mul_f32_e32 v111, 0xbfb8aa3b, v111
	v_mul_f32_e32 v112, 0xbfb8aa3b, v112
	v_mul_f32_e32 v113, 0xbfb8aa3b, v113
	v_mul_f32_e32 v114, 0xbfb8aa3b, v114
	v_mul_f32_e32 v115, 0xbfb8aa3b, v115
	v_exp_f32_e32 v108, v108
	v_exp_f32_e32 v109, v109
	v_exp_f32_e32 v110, v110
	v_exp_f32_e32 v111, v111
	v_exp_f32_e32 v112, v112
	v_exp_f32_e32 v113, v113
	v_exp_f32_e32 v114, v114
	v_exp_f32_e32 v115, v115
	v_add_f32_e32 v108, 1.0, v108
	v_add_f32_e32 v109, 1.0, v109
	v_add_f32_e32 v110, 1.0, v110
	v_add_f32_e32 v111, 1.0, v111
	v_add_f32_e32 v112, 1.0, v112
	v_add_f32_e32 v113, 1.0, v113
	v_add_f32_e32 v114, 1.0, v114
	v_add_f32_e32 v115, 1.0, v115
	v_rcp_f32_e32 v108, v108
	v_rcp_f32_e32 v109, v109
	v_rcp_f32_e32 v110, v110
	v_rcp_f32_e32 v111, v111
	v_rcp_f32_e32 v112, v112
	v_rcp_f32_e32 v113, v113
	v_rcp_f32_e32 v114, v114
	v_rcp_f32_e32 v115, v115
	v_mul_f32_e32 v108, 0xbf60028b, v108
	v_mul_f32_e32 v109, 0xbf60028b, v109
	v_mul_f32_e32 v110, 0xbf60028b, v110
	v_mul_f32_e32 v111, 0xbf60028b, v111
	v_cvt_pk_bf16_f32 v116, v112, v113
	v_cvt_pk_bf16_f32 v117, v114, v115
	v_exp_f32_e32 v108, v108
	v_exp_f32_e32 v109, v109
	v_exp_f32_e32 v110, v110
	v_exp_f32_e32 v111, v111
	v_cvt_pk_bf16_f32 v118, v104, v105
	v_cvt_pk_bf16_f32 v119, v106, v107
	global_store_dwordx2 v136, v[116:117], s[44:45]
	global_store_dwordx2 v136, v[118:119], s[46:47]
	global_store_dwordx4 v135, v[108:111], s[54:55]
	v_add_u32_e32 v136, 32, v136
	v_add_u32_e32 v135, 64, v135
	global_load_dwordx4 v[16:19], v132, s[24:25]
	global_load_dwordx4 v[20:23], v132, s[24:25] offset:64
	global_load_dwordx4 v[24:27], v132, s[40:41]
	global_load_dwordx4 v[28:31], v132, s[40:41] offset:64
	global_load_dwordx4 v[32:35], v133, s[42:43]
	global_load_dwordx4 v[36:39], v133, s[42:43] offset:64
	global_load_dwordx4 v[40:43], v133, s[42:43] offset:128
	global_load_dwordx4 v[44:47], v133, s[42:43] offset:192
	global_load_dwordx4 v[48:51], v134, s[20:21]
	global_load_dwordx4 v[52:55], v134, s[22:23]
	s_waitcnt vmcnt(13)
	v_mfma_f32_16x16x32_bf16 v[96:99], v[56:59], v[184:187], 0
	v_mfma_f32_16x16x32_bf16 v[100:103], v[64:67], v[192:195], 0
	v_mfma_f32_16x16x32_bf16 v[104:107], v[72:75], v[200:203], 0
	v_mfma_f32_16x16x32_bf16 v[96:99], v[60:63], v[188:191], v[96:99]
	v_mfma_f32_16x16x32_bf16 v[100:103], v[68:71], v[196:199], v[100:103]
	v_mfma_f32_16x16x32_bf16 v[104:107], v[76:79], v[204:207], v[104:107]
	v_mfma_f32_16x16x32_bf16 v[104:107], v[80:83], v[208:211], v[104:107]
	v_mfma_f32_16x16x32_bf16 v[104:107], v[84:87], v[212:215], v[104:107]
	v_add_u32_e32 v132, 0x800, v132
	v_add_u32_e32 v133, 0x1000, v133
	v_add_u32_e32 v134, 64, v134
	s_nop 4
	v_add_f32_e32 v108, v88, v96
	v_add_f32_e32 v109, v89, v97
	v_add_f32_e32 v110, v90, v98
	v_add_f32_e32 v111, v91, v99
	v_add_f32_e32 v112, v92, v100
	v_add_f32_e32 v113, v93, v101
	v_add_f32_e32 v114, v94, v102
	v_add_f32_e32 v115, v95, v103
	v_mul_f32_e32 v108, 0xbfb8aa3b, v108
	v_mul_f32_e32 v109, 0xbfb8aa3b, v109
	v_mul_f32_e32 v110, 0xbfb8aa3b, v110
	v_mul_f32_e32 v111, 0xbfb8aa3b, v111
	v_mul_f32_e32 v112, 0xbfb8aa3b, v112
	v_mul_f32_e32 v113, 0xbfb8aa3b, v113
	v_mul_f32_e32 v114, 0xbfb8aa3b, v114
	v_mul_f32_e32 v115, 0xbfb8aa3b, v115
	v_exp_f32_e32 v108, v108
	v_exp_f32_e32 v109, v109
	v_exp_f32_e32 v110, v110
	v_exp_f32_e32 v111, v111
	v_exp_f32_e32 v112, v112
	v_exp_f32_e32 v113, v113
	v_exp_f32_e32 v114, v114
	v_exp_f32_e32 v115, v115
	v_add_f32_e32 v108, 1.0, v108
	v_add_f32_e32 v109, 1.0, v109
	v_add_f32_e32 v110, 1.0, v110
	v_add_f32_e32 v111, 1.0, v111
	v_add_f32_e32 v112, 1.0, v112
	v_add_f32_e32 v113, 1.0, v113
	v_add_f32_e32 v114, 1.0, v114
	v_add_f32_e32 v115, 1.0, v115
	v_rcp_f32_e32 v108, v108
	v_rcp_f32_e32 v109, v109
	v_rcp_f32_e32 v110, v110
	v_rcp_f32_e32 v111, v111
	v_rcp_f32_e32 v112, v112
	v_rcp_f32_e32 v113, v113
	v_rcp_f32_e32 v114, v114
	v_rcp_f32_e32 v115, v115
	v_mul_f32_e32 v108, 0xbf60028b, v108
	v_mul_f32_e32 v109, 0xbf60028b, v109
	v_mul_f32_e32 v110, 0xbf60028b, v110
	v_mul_f32_e32 v111, 0xbf60028b, v111
	v_cvt_pk_bf16_f32 v116, v112, v113
	v_cvt_pk_bf16_f32 v117, v114, v115
	v_exp_f32_e32 v108, v108
	v_exp_f32_e32 v109, v109
	v_exp_f32_e32 v110, v110
	v_exp_f32_e32 v111, v111
	v_cvt_pk_bf16_f32 v118, v104, v105
	v_cvt_pk_bf16_f32 v119, v106, v107
	global_store_dwordx2 v136, v[116:117], s[44:45]
	global_store_dwordx2 v136, v[118:119], s[46:47]
	global_store_dwordx4 v135, v[108:111], s[54:55]
	v_add_u32_e32 v136, 32, v136
	v_add_u32_e32 v135, 64, v135
	s_movk_i32 s2, 14
; __device__ __forceinline__ unsigned pk2(float lo, float hi) { f32x2 v = {lo, hi}; bf16x2_t b = __builtin_convertvector(v, bf16x2_t); return __builtin_bit_cast(unsigned, b); }
; __device__ __forceinline__ float sigmoidf_(float x) { return frcp(1.f + fexp2(-1.4426950408889634f * x)); }
; __device__ __forceinline__ void phase_lora(const Ctx& p, LAS unsigned char* lds) {
;     ...
;         auto tile = [&](const WF& f, int nt) {
;             f32x4 aw = (f32x4){0.f, 0.f, 0.f, 0.f}, aa = aw, ag = aw;
; #pragma unroll
;             for (int ks = 0; ks < 2; ++ks) { aw = __builtin_amdgcn_mfma_f32_16x16x32_bf16(f.w[ks], bx[ks], aw, 0, 0, 0); aa = __builtin_amdgcn_mfma_f32_16x16x32_bf16(f.a[ks], bx[2 + ks], aa, 0, 0, 0); }
; #pragma unroll
;             for (int ks = 0; ks < 4; ++ks) ag = __builtin_amdgcn_mfma_f32_16x16x32_bf16(f.gq[ks], bx[4 + ks], ag, 0, 0, 0);
;             const int c = nt * 16 + 4 * g;
;             f32x4 dec; float av[4];
; #pragma unroll
;             for (int e = 0; e < 4; ++e) {
;                 const float x = f.w0[e] + aw[e];
;                 const float sp = fmaxf(-x, 0.f) + log1pf(expf(-fabsf(x)));
;                 dec[e] = expf(-expf(-sp - 0.5f));
;                 av[e] = sigmoidf_(f.a0[e] + aa[e]);
;             }
;             *(f32x4*)(DEC + (size_t)row * 512 + c) = dec;
;             *(u32x2*)(AB + (size_t)row * 512 + c) = (u32x2){pk2(av[0], av[1]), pk2(av[2], av[3])};
;             *(u32x2*)(GG + (size_t)row * 512 + c) = (u32x2){pk2(ag[0], ag[1]), pk2(ag[2], ag[3])};
;         };
;         WF fa, fb;
;         ldw(fa, 0);
; #pragma unroll 1
;         for (int nt = 0; nt < 32; nt += 2) {
;             ldw(fb, nt + 1);
;             tile(fa, nt);
;             ldw(fa, (nt + 2) & 31);
;             tile(fb, nt + 1);
;         }
.Llora_nt:
	global_load_dwordx4 v[56:59], v132, s[24:25]
	global_load_dwordx4 v[60:63], v132, s[24:25] offset:64
	global_load_dwordx4 v[64:67], v132, s[40:41]
	global_load_dwordx4 v[68:71], v132, s[40:41] offset:64
	global_load_dwordx4 v[72:75], v133, s[42:43]
	global_load_dwordx4 v[76:79], v133, s[42:43] offset:64
	global_load_dwordx4 v[80:83], v133, s[42:43] offset:128
	global_load_dwordx4 v[84:87], v133, s[42:43] offset:192
	global_load_dwordx4 v[88:91], v134, s[20:21]
	global_load_dwordx4 v[92:95], v134, s[22:23]
	s_waitcnt vmcnt(13)
	v_mfma_f32_16x16x32_bf16 v[96:99], v[16:19], v[184:187], 0
	v_mfma_f32_16x16x32_bf16 v[100:103], v[24:27], v[192:195], 0
	v_mfma_f32_16x16x32_bf16 v[104:107], v[32:35], v[200:203], 0
	v_mfma_f32_16x16x32_bf16 v[96:99], v[20:23], v[188:191], v[96:99]
	v_mfma_f32_16x16x32_bf16 v[100:103], v[28:31], v[196:199], v[100:103]
	v_mfma_f32_16x16x32_bf16 v[104:107], v[36:39], v[204:207], v[104:107]
	v_mfma_f32_16x16x32_bf16 v[104:107], v[40:43], v[208:211], v[104:107]
	v_mfma_f32_16x16x32_bf16 v[104:107], v[44:47], v[212:215], v[104:107]
	v_add_u32_e32 v132, 0x800, v132
	v_add_u32_e32 v133, 0x1000, v133
	v_add_u32_e32 v134, 64, v134
	s_nop 4
	v_add_f32_e32 v108, v48, v96
	v_add_f32_e32 v109, v49, v97
	v_add_f32_e32 v110, v50, v98
	v_add_f32_e32 v111, v51, v99
	v_add_f32_e32 v112, v52, v100
	v_add_f32_e32 v113, v53, v101
	v_add_f32_e32 v114, v54, v102
	v_add_f32_e32 v115, v55, v103
	v_mul_f32_e32 v108, 0xbfb8aa3b, v108
	v_mul_f32_e32 v109, 0xbfb8aa3b, v109
	v_mul_f32_e32 v110, 0xbfb8aa3b, v110
	v_mul_f32_e32 v111, 0xbfb8aa3b, v111
	v_mul_f32_e32 v112, 0xbfb8aa3b, v112
	v_mul_f32_e32 v113, 0xbfb8aa3b, v113
	v_mul_f32_e32 v114, 0xbfb8aa3b, v114
	v_mul_f32_e32 v115, 0xbfb8aa3b, v115
	v_exp_f32_e32 v108, v108
	v_exp_f32_e32 v109, v109
	v_exp_f32_e32 v110, v110
	v_exp_f32_e32 v111, v111
	v_exp_f32_e32 v112, v112
	v_exp_f32_e32 v113, v113
	v_exp_f32_e32 v114, v114
	v_exp_f32_e32 v115, v115
	v_add_f32_e32 v108, 1.0, v108
	v_add_f32_e32 v109, 1.0, v109
	v_add_f32_e32 v110, 1.0, v110
	v_add_f32_e32 v111, 1.0, v111
	v_add_f32_e32 v112, 1.0, v112
	v_add_f32_e32 v113, 1.0, v113
	v_add_f32_e32 v114, 1.0, v114
	v_add_f32_e32 v115, 1.0, v115
	v_rcp_f32_e32 v108, v108
	v_rcp_f32_e32 v109, v109
	v_rcp_f32_e32 v110, v110
	v_rcp_f32_e32 v111, v111
	v_rcp_f32_e32 v112, v112
	v_rcp_f32_e32 v113, v113
	v_rcp_f32_e32 v114, v114
	v_rcp_f32_e32 v115, v115
	v_mul_f32_e32 v108, 0xbf60028b, v108
	v_mul_f32_e32 v109, 0xbf60028b, v109
	v_mul_f32_e32 v110, 0xbf60028b, v110
	v_mul_f32_e32 v111, 0xbf60028b, v111
	v_cvt_pk_bf16_f32 v116, v112, v113
	v_cvt_pk_bf16_f32 v117, v114, v115
	v_exp_f32_e32 v108, v108
	v_exp_f32_e32 v109, v109
	v_exp_f32_e32 v110, v110
	v_exp_f32_e32 v111, v111
	v_cvt_pk_bf16_f32 v118, v104, v105
	v_cvt_pk_bf16_f32 v119, v106, v107
	global_store_dwordx2 v136, v[116:117], s[44:45]
	global_store_dwordx2 v136, v[118:119], s[46:47]
	global_store_dwordx4 v135, v[108:111], s[54:55]
	v_add_u32_e32 v136, 32, v136
	v_add_u32_e32 v135, 64, v135
	global_load_dwordx4 v[16:19], v132, s[24:25]
	global_load_dwordx4 v[20:23], v132, s[24:25] offset:64
	global_load_dwordx4 v[24:27], v132, s[40:41]
	global_load_dwordx4 v[28:31], v132, s[40:41] offset:64
	global_load_dwordx4 v[32:35], v133, s[42:43]
	global_load_dwordx4 v[36:39], v133, s[42:43] offset:64
	global_load_dwordx4 v[40:43], v133, s[42:43] offset:128
	global_load_dwordx4 v[44:47], v133, s[42:43] offset:192
	global_load_dwordx4 v[48:51], v134, s[20:21]
	global_load_dwordx4 v[52:55], v134, s[22:23]
	s_waitcnt vmcnt(13)
	v_mfma_f32_16x16x32_bf16 v[96:99], v[56:59], v[184:187], 0
	v_mfma_f32_16x16x32_bf16 v[100:103], v[64:67], v[192:195], 0
	v_mfma_f32_16x16x32_bf16 v[104:107], v[72:75], v[200:203], 0
	v_mfma_f32_16x16x32_bf16 v[96:99], v[60:63], v[188:191], v[96:99]
	v_mfma_f32_16x16x32_bf16 v[100:103], v[68:71], v[196:199], v[100:103]
	v_mfma_f32_16x16x32_bf16 v[104:107], v[76:79], v[204:207], v[104:107]
	v_mfma_f32_16x16x32_bf16 v[104:107], v[80:83], v[208:211], v[104:107]
	v_mfma_f32_16x16x32_bf16 v[104:107], v[84:87], v[212:215], v[104:107]
	v_add_u32_e32 v132, 0x800, v132
	v_add_u32_e32 v133, 0x1000, v133
	v_add_u32_e32 v134, 64, v134
	s_nop 4
	v_add_f32_e32 v108, v88, v96
	v_add_f32_e32 v109, v89, v97
	v_add_f32_e32 v110, v90, v98
	v_add_f32_e32 v111, v91, v99
	v_add_f32_e32 v112, v92, v100
	v_add_f32_e32 v113, v93, v101
	v_add_f32_e32 v114, v94, v102
	v_add_f32_e32 v115, v95, v103
	v_mul_f32_e32 v108, 0xbfb8aa3b, v108
	v_mul_f32_e32 v109, 0xbfb8aa3b, v109
	v_mul_f32_e32 v110, 0xbfb8aa3b, v110
	v_mul_f32_e32 v111, 0xbfb8aa3b, v111
	v_mul_f32_e32 v112, 0xbfb8aa3b, v112
	v_mul_f32_e32 v113, 0xbfb8aa3b, v113
	v_mul_f32_e32 v114, 0xbfb8aa3b, v114
	v_mul_f32_e32 v115, 0xbfb8aa3b, v115
	v_exp_f32_e32 v108, v108
	v_exp_f32_e32 v109, v109
	v_exp_f32_e32 v110, v110
	v_exp_f32_e32 v111, v111
	v_exp_f32_e32 v112, v112
	v_exp_f32_e32 v113, v113
	v_exp_f32_e32 v114, v114
	v_exp_f32_e32 v115, v115
	v_add_f32_e32 v108, 1.0, v108
	v_add_f32_e32 v109, 1.0, v109
	v_add_f32_e32 v110, 1.0, v110
	v_add_f32_e32 v111, 1.0, v111
	v_add_f32_e32 v112, 1.0, v112
	v_add_f32_e32 v113, 1.0, v113
	v_add_f32_e32 v114, 1.0, v114
	v_add_f32_e32 v115, 1.0, v115
	v_rcp_f32_e32 v108, v108
	v_rcp_f32_e32 v109, v109
	v_rcp_f32_e32 v110, v110
	v_rcp_f32_e32 v111, v111
	v_rcp_f32_e32 v112, v112
	v_rcp_f32_e32 v113, v113
	v_rcp_f32_e32 v114, v114
	v_rcp_f32_e32 v115, v115
	v_mul_f32_e32 v108, 0xbf60028b, v108
	v_mul_f32_e32 v109, 0xbf60028b, v109
	v_mul_f32_e32 v110, 0xbf60028b, v110
	v_mul_f32_e32 v111, 0xbf60028b, v111
	v_cvt_pk_bf16_f32 v116, v112, v113
	v_cvt_pk_bf16_f32 v117, v114, v115
	v_exp_f32_e32 v108, v108
	v_exp_f32_e32 v109, v109
	v_exp_f32_e32 v110, v110
	v_exp_f32_e32 v111, v111
	v_cvt_pk_bf16_f32 v118, v104, v105
	v_cvt_pk_bf16_f32 v119, v106, v107
	global_store_dwordx2 v136, v[116:117], s[44:45]
	global_store_dwordx2 v136, v[118:119], s[46:47]
	global_store_dwordx4 v135, v[108:111], s[54:55]
	v_add_u32_e32 v136, 32, v136
	v_add_u32_e32 v135, 64, v135
	s_sub_u32 s2, s2, 1
	s_cmp_lg_u32 s2, 0
	s_cbranch_scc1 .Llora_nt
; __device__ __forceinline__ void phase_lora(const Ctx& p, LAS unsigned char* lds) {
;     ...
;     for (int it = blockIdx.x + gridDim.x * wave; it < MR / 16; it += gridDim.x * 8) {
;     ...
; #pragma unroll 1
;         for (int nt = 0; nt < 32; nt += 2) {
;             ldw(fb, nt + 1);
;             tile(fa, nt);
;             ldw(fa, (nt + 2) & 31);
;             tile(fb, nt + 1);
;         }
;         asm volatile("s_waitcnt lgkmcnt(0)" ::: "memory");
;     }
	global_load_dwordx4 v[56:59], v132, s[24:25]
	global_load_dwordx4 v[60:63], v132, s[24:25] offset:64
	global_load_dwordx4 v[64:67], v132, s[40:41]
	global_load_dwordx4 v[68:71], v132, s[40:41] offset:64
	global_load_dwordx4 v[72:75], v133, s[42:43]
	global_load_dwordx4 v[76:79], v133, s[42:43] offset:64
	global_load_dwordx4 v[80:83], v133, s[42:43] offset:128
	global_load_dwordx4 v[84:87], v133, s[42:43] offset:192
	global_load_dwordx4 v[88:91], v134, s[20:21]
	global_load_dwordx4 v[92:95], v134, s[22:23]
	s_waitcnt vmcnt(13)
	v_mfma_f32_16x16x32_bf16 v[96:99], v[16:19], v[184:187], 0
	v_mfma_f32_16x16x32_bf16 v[100:103], v[24:27], v[192:195], 0
	v_mfma_f32_16x16x32_bf16 v[104:107], v[32:35], v[200:203], 0
	v_mfma_f32_16x16x32_bf16 v[96:99], v[20:23], v[188:191], v[96:99]
	v_mfma_f32_16x16x32_bf16 v[100:103], v[28:31], v[196:199], v[100:103]
	v_mfma_f32_16x16x32_bf16 v[104:107], v[36:39], v[204:207], v[104:107]
	v_mfma_f32_16x16x32_bf16 v[104:107], v[40:43], v[208:211], v[104:107]
	v_mfma_f32_16x16x32_bf16 v[104:107], v[44:47], v[212:215], v[104:107]
	v_add_u32_e32 v132, 0x800, v132
	v_add_u32_e32 v133, 0x1000, v133
	v_add_u32_e32 v134, 64, v134
	s_nop 4
	v_add_f32_e32 v108, v48, v96
	v_add_f32_e32 v109, v49, v97
	v_add_f32_e32 v110, v50, v98
	v_add_f32_e32 v111, v51, v99
	v_add_f32_e32 v112, v52, v100
	v_add_f32_e32 v113, v53, v101
	v_add_f32_e32 v114, v54, v102
	v_add_f32_e32 v115, v55, v103
	v_mul_f32_e32 v108, 0xbfb8aa3b, v108
	v_mul_f32_e32 v109, 0xbfb8aa3b, v109
	v_mul_f32_e32 v110, 0xbfb8aa3b, v110
	v_mul_f32_e32 v111, 0xbfb8aa3b, v111
	v_mul_f32_e32 v112, 0xbfb8aa3b, v112
	v_mul_f32_e32 v113, 0xbfb8aa3b, v113
	v_mul_f32_e32 v114, 0xbfb8aa3b, v114
	v_mul_f32_e32 v115, 0xbfb8aa3b, v115
	v_exp_f32_e32 v108, v108
	v_exp_f32_e32 v109, v109
	v_exp_f32_e32 v110, v110
	v_exp_f32_e32 v111, v111
	v_exp_f32_e32 v112, v112
	v_exp_f32_e32 v113, v113
	v_exp_f32_e32 v114, v114
	v_exp_f32_e32 v115, v115
	v_add_f32_e32 v108, 1.0, v108
	v_add_f32_e32 v109, 1.0, v109
	v_add_f32_e32 v110, 1.0, v110
	v_add_f32_e32 v111, 1.0, v111
	v_add_f32_e32 v112, 1.0, v112
	v_add_f32_e32 v113, 1.0, v113
	v_add_f32_e32 v114, 1.0, v114
	v_add_f32_e32 v115, 1.0, v115
	v_rcp_f32_e32 v108, v108
	v_rcp_f32_e32 v109, v109
	v_rcp_f32_e32 v110, v110
	v_rcp_f32_e32 v111, v111
	v_rcp_f32_e32 v112, v112
	v_rcp_f32_e32 v113, v113
	v_rcp_f32_e32 v114, v114
	v_rcp_f32_e32 v115, v115
	v_mul_f32_e32 v108, 0xbf60028b, v108
	v_mul_f32_e32 v109, 0xbf60028b, v109
	v_mul_f32_e32 v110, 0xbf60028b, v110
	v_mul_f32_e32 v111, 0xbf60028b, v111
	v_cvt_pk_bf16_f32 v116, v112, v113
	v_cvt_pk_bf16_f32 v117, v114, v115
	v_exp_f32_e32 v108, v108
	v_exp_f32_e32 v109, v109
	v_exp_f32_e32 v110, v110
	v_exp_f32_e32 v111, v111
	v_cvt_pk_bf16_f32 v118, v104, v105
	v_cvt_pk_bf16_f32 v119, v106, v107
	global_store_dwordx2 v136, v[116:117], s[44:45]
	global_store_dwordx2 v136, v[118:119], s[46:47]
	global_store_dwordx4 v135, v[108:111], s[54:55]
	v_add_u32_e32 v136, 32, v136
	v_add_u32_e32 v135, 64, v135
	s_waitcnt vmcnt(3)
	v_mfma_f32_16x16x32_bf16 v[96:99], v[56:59], v[184:187], 0
	v_mfma_f32_16x16x32_bf16 v[100:103], v[64:67], v[192:195], 0
	v_mfma_f32_16x16x32_bf16 v[104:107], v[72:75], v[200:203], 0
	v_mfma_f32_16x16x32_bf16 v[96:99], v[60:63], v[188:191], v[96:99]
	v_mfma_f32_16x16x32_bf16 v[100:103], v[68:71], v[196:199], v[100:103]
	v_mfma_f32_16x16x32_bf16 v[104:107], v[76:79], v[204:207], v[104:107]
	v_mfma_f32_16x16x32_bf16 v[104:107], v[80:83], v[208:211], v[104:107]
	v_mfma_f32_16x16x32_bf16 v[104:107], v[84:87], v[212:215], v[104:107]
	v_add_u32_e32 v132, 0x800, v132
	v_add_u32_e32 v133, 0x1000, v133
	v_add_u32_e32 v134, 64, v134
	s_nop 4
	v_add_f32_e32 v108, v88, v96
	v_add_f32_e32 v109, v89, v97
	v_add_f32_e32 v110, v90, v98
	v_add_f32_e32 v111, v91, v99
	v_add_f32_e32 v112, v92, v100
	v_add_f32_e32 v113, v93, v101
	v_add_f32_e32 v114, v94, v102
	v_add_f32_e32 v115, v95, v103
	v_mul_f32_e32 v108, 0xbfb8aa3b, v108
	v_mul_f32_e32 v109, 0xbfb8aa3b, v109
	v_mul_f32_e32 v110, 0xbfb8aa3b, v110
	v_mul_f32_e32 v111, 0xbfb8aa3b, v111
	v_mul_f32_e32 v112, 0xbfb8aa3b, v112
	v_mul_f32_e32 v113, 0xbfb8aa3b, v113
	v_mul_f32_e32 v114, 0xbfb8aa3b, v114
	v_mul_f32_e32 v115, 0xbfb8aa3b, v115
	v_exp_f32_e32 v108, v108
	v_exp_f32_e32 v109, v109
	v_exp_f32_e32 v110, v110
	v_exp_f32_e32 v111, v111
	v_exp_f32_e32 v112, v112
	v_exp_f32_e32 v113, v113
	v_exp_f32_e32 v114, v114
	v_exp_f32_e32 v115, v115
	v_add_f32_e32 v108, 1.0, v108
	v_add_f32_e32 v109, 1.0, v109
	v_add_f32_e32 v110, 1.0, v110
	v_add_f32_e32 v111, 1.0, v111
	v_add_f32_e32 v112, 1.0, v112
	v_add_f32_e32 v113, 1.0, v113
	v_add_f32_e32 v114, 1.0, v114
	v_add_f32_e32 v115, 1.0, v115
	v_rcp_f32_e32 v108, v108
	v_rcp_f32_e32 v109, v109
	v_rcp_f32_e32 v110, v110
	v_rcp_f32_e32 v111, v111
	v_rcp_f32_e32 v112, v112
	v_rcp_f32_e32 v113, v113
	v_rcp_f32_e32 v114, v114
	v_rcp_f32_e32 v115, v115
	v_mul_f32_e32 v108, 0xbf60028b, v108
	v_mul_f32_e32 v109, 0xbf60028b, v109
	v_mul_f32_e32 v110, 0xbf60028b, v110
	v_mul_f32_e32 v111, 0xbf60028b, v111
	v_cvt_pk_bf16_f32 v116, v112, v113
	v_cvt_pk_bf16_f32 v117, v114, v115
	v_exp_f32_e32 v108, v108
	v_exp_f32_e32 v109, v109
	v_exp_f32_e32 v110, v110
	v_exp_f32_e32 v111, v111
	v_cvt_pk_bf16_f32 v118, v104, v105
	v_cvt_pk_bf16_f32 v119, v106, v107
	global_store_dwordx2 v136, v[116:117], s[44:45]
	global_store_dwordx2 v136, v[118:119], s[46:47]
	global_store_dwordx4 v135, v[108:111], s[54:55]
	v_add_u32_e32 v136, 32, v136
	v_add_u32_e32 v135, 64, v135
	s_lshl_b32 s2, s38, 3
	s_add_i32 s26, s26, s2
	s_branch .Llora_item
